# tile remap (per-XCD contiguous GEMM tiles) + final RMS-norm phase hand-pipelined (hoisted final_g, ping-pong rows, counted vmcnt)
# speedup vs baseline: 1.0035x; 1.0016x over previous
; DI float shx(float v, int lane, int m) { return __int_as_float(__builtin_amdgcn_ds_bpermute((lane ^ m) << 2, __float_as_int(v))); }
; DI void phase_final(const int wv_, const Params& p) {
;     ...
;   for (int R = bid_ * 8 + wave; R < NB * SEQ; R += nblk_ * 8) {
;     float4* row = (float4*)(p.out + (size_t)R * 1024);
;     float4 v[4]; float ss = 0.f;
; #pragma unroll
;     for (int i = 0; i < 4; ++i) { v[i] = row[lane + i * 64]; ss += v[i].x * v[i].x + v[i].y * v[i].y + v[i].z * v[i].z + v[i].w * v[i].w; }
; #pragma unroll
;     for (int o = 32; o >= 1; o >>= 1) ss += shx(ss, lane, o);
;     float sc = rsqrtf(ss * (1.f / 1024.f) + 1e-6f);
; #pragma unroll
;     for (int i = 0; i < 4; ++i) {
;       float4 gg = ((const float4*)p.final_g)[lane + i * 64];
;       row[lane + i * 64] = make_float4(v[i].x * sc * gg.x, v[i].y * sc * gg.y, v[i].z * sc * gg.z, v[i].w * sc * gg.w);
;     }
.LBB0_1061:
	s_mov_b32 s0, 0
	s_nop 0
	v_mbcnt_lo_u32_b32 v0, -1, s0
	v_mbcnt_hi_u32_b32 v0, -1, v0
	v_add_u32_e32 v0, s33, v0
	s_lshl_b32 s2, s16, 3
	v_ashrrev_i32_e32 v2, 6, v0
	v_add_u32_e32 v4, s2, v2
	s_mov_b32 s0, 0x8000
	v_cmp_gt_i32_e32 vcc, s0, v4
	s_and_saveexec_b64 s[0:1], vcc
	s_cbranch_execz .LBB0_1064
	v_ashrrev_i32_e32 v3, 31, v2
	s_ashr_i32 s3, s2, 31
	v_and_b32_e32 v0, 63, v0
	v_lshl_add_u64 v[2:3], v[2:3], 0, s[2:3]
	v_lshlrev_b32_e32 v12, 4, v0
	v_lshlrev_b64 v[2:3], 12, v[2:3]
	s_lshl_b32 s0, s17, 3
	v_or_b32_e32 v2, v2, v12
	v_lshlrev_b32_e32 v1, 2, v0
	v_mov_b32_e32 v13, 0
	v_lshl_add_u64 v[2:3], s[42:43], 0, v[2:3]
	s_mov_b64 s[2:3], 0x800
	s_ashr_i32 s1, s0, 31
	v_xor_b32_e32 v5, 0x80, v1
	v_xor_b32_e32 v6, 64, v1
	v_xor_b32_e32 v7, 32, v1
	v_xor_b32_e32 v8, 16, v1
	v_xor_b32_e32 v9, 8, v1
	v_xor_b32_e32 v10, 4, v1
	v_lshl_add_u64 v[0:1], s[60:61], 0, v[12:13]
	v_lshl_add_u64 v[2:3], v[2:3], 0, s[2:3]
	s_lshl_b64 s[2:3], s[0:1], 12
	s_mov_b64 s[4:5], 0
	v_mov_b32_e32 v11, 0x358637bd
	s_mov_b32 s1, 0x800000
	s_movk_i32 s6, 0x7fff
	v_readfirstlane_b32 s7, v4
	s_mov_b32 s9, 0x8000
	global_load_dwordx4 v[48:51], v[0:1], off
	global_load_dwordx4 v[52:55], v[0:1], off offset:1024
	global_load_dwordx4 v[56:59], v[0:1], off offset:2048
	global_load_dwordx4 v[60:63], v[0:1], off offset:3072
	global_load_dwordx4 v[12:15], v[2:3], off offset:-2048
	global_load_dwordx4 v[16:19], v[2:3], off offset:-1024
	global_load_dwordx4 v[20:23], v[2:3], off
	global_load_dwordx4 v[24:27], v[2:3], off offset:1024
.Lfin_A:
	s_add_i32 s7, s7, s0
	s_cmp_lt_i32 s7, s9
	s_cbranch_scc0 .Lfin_A_last
	v_lshl_add_u64 v[64:65], v[2:3], 0, s[2:3]
	global_load_dwordx4 v[68:71], v[64:65], off offset:-2048
	global_load_dwordx4 v[72:75], v[64:65], off offset:-1024
	global_load_dwordx4 v[76:79], v[64:65], off
	global_load_dwordx4 v[80:83], v[64:65], off offset:1024
	s_waitcnt vmcnt(4)
	v_mul_f32_e32 v34, v12, v12
	v_fmac_f32_e32 v34, v13, v13
	v_fmac_f32_e32 v34, v14, v14
	v_fmac_f32_e32 v34, v15, v15
	v_fmac_f32_e32 v34, v16, v16
	v_fmac_f32_e32 v34, v17, v17
	v_fmac_f32_e32 v34, v18, v18
	v_fmac_f32_e32 v34, v19, v19
	v_fmac_f32_e32 v34, v20, v20
	v_fmac_f32_e32 v34, v21, v21
	v_fmac_f32_e32 v34, v22, v22
	v_fmac_f32_e32 v34, v23, v23
	v_fmac_f32_e32 v34, v24, v24
	v_fmac_f32_e32 v34, v25, v25
	v_fmac_f32_e32 v34, v26, v26
	v_fmac_f32_e32 v34, v27, v27
	v_mov_b32_e32 v32, v34
	ds_bpermute_b32 v33, v5, v32
	s_waitcnt lgkmcnt(0)
	v_add_f32_e32 v32, v32, v33
	ds_bpermute_b32 v33, v6, v32
	s_waitcnt lgkmcnt(0)
	v_add_f32_e32 v32, v32, v33
	ds_bpermute_b32 v33, v7, v32
	s_waitcnt lgkmcnt(0)
	v_add_f32_e32 v32, v32, v33
	ds_bpermute_b32 v33, v8, v32
	s_waitcnt lgkmcnt(0)
	v_add_f32_e32 v32, v32, v33
	ds_bpermute_b32 v33, v9, v32
	s_waitcnt lgkmcnt(0)
	v_add_f32_e32 v32, v32, v33
	ds_bpermute_b32 v33, v10, v32
	s_waitcnt lgkmcnt(0)
	v_add_f32_e32 v32, v32, v33
	v_fmamk_f32 v32, v32, 0x3a800000, v11
	v_mul_f32_e32 v33, 0x4b800000, v32
	v_cmp_gt_f32_e32 vcc, s1, v32
	s_nop 1
	v_cndmask_b32_e32 v32, v32, v33, vcc
	v_rsq_f32_e32 v32, v32
	s_nop 0
	v_mul_f32_e32 v33, 0x45800000, v32
	v_cndmask_b32_e32 v32, v32, v33, vcc
	s_nop 0
	v_pk_mul_f32 v[12:13], v[12:13], v[32:33] op_sel_hi:[1,0]
	v_pk_mul_f32 v[14:15], v[14:15], v[32:33] op_sel_hi:[1,0]
	v_pk_mul_f32 v[12:13], v[48:49], v[12:13]
	v_pk_mul_f32 v[14:15], v[50:51], v[14:15]
	global_store_dwordx4 v[2:3], v[12:15], off offset:-2048
	v_pk_mul_f32 v[16:17], v[16:17], v[32:33] op_sel_hi:[1,0]
	v_pk_mul_f32 v[18:19], v[18:19], v[32:33] op_sel_hi:[1,0]
	v_pk_mul_f32 v[16:17], v[52:53], v[16:17]
	v_pk_mul_f32 v[18:19], v[54:55], v[18:19]
	global_store_dwordx4 v[2:3], v[16:19], off offset:-1024
	v_pk_mul_f32 v[20:21], v[20:21], v[32:33] op_sel_hi:[1,0]
	v_pk_mul_f32 v[22:23], v[22:23], v[32:33] op_sel_hi:[1,0]
	v_pk_mul_f32 v[20:21], v[56:57], v[20:21]
	v_pk_mul_f32 v[22:23], v[58:59], v[22:23]
	global_store_dwordx4 v[2:3], v[20:23], off
	v_pk_mul_f32 v[24:25], v[24:25], v[32:33] op_sel_hi:[1,0]
	v_pk_mul_f32 v[26:27], v[26:27], v[32:33] op_sel_hi:[1,0]
	v_pk_mul_f32 v[24:25], v[60:61], v[24:25]
	v_pk_mul_f32 v[26:27], v[62:63], v[26:27]
	global_store_dwordx4 v[2:3], v[24:27], off offset:1024
	s_add_i32 s7, s7, s0
	s_cmp_lt_i32 s7, s9
	s_cbranch_scc0 .Lfin_B_last
	v_lshl_add_u64 v[2:3], v[64:65], 0, s[2:3]
	global_load_dwordx4 v[12:15], v[2:3], off offset:-2048
	global_load_dwordx4 v[16:19], v[2:3], off offset:-1024
	global_load_dwordx4 v[20:23], v[2:3], off
	global_load_dwordx4 v[24:27], v[2:3], off offset:1024
	s_waitcnt vmcnt(4)
	v_mul_f32_e32 v34, v68, v68
	v_fmac_f32_e32 v34, v69, v69
	v_fmac_f32_e32 v34, v70, v70
	v_fmac_f32_e32 v34, v71, v71
	v_fmac_f32_e32 v34, v72, v72
	v_fmac_f32_e32 v34, v73, v73
	v_fmac_f32_e32 v34, v74, v74
	v_fmac_f32_e32 v34, v75, v75
	v_fmac_f32_e32 v34, v76, v76
	v_fmac_f32_e32 v34, v77, v77
	v_fmac_f32_e32 v34, v78, v78
	v_fmac_f32_e32 v34, v79, v79
	v_fmac_f32_e32 v34, v80, v80
	v_fmac_f32_e32 v34, v81, v81
	v_fmac_f32_e32 v34, v82, v82
	v_fmac_f32_e32 v34, v83, v83
	v_mov_b32_e32 v32, v34
	ds_bpermute_b32 v33, v5, v32
	s_waitcnt lgkmcnt(0)
	v_add_f32_e32 v32, v32, v33
	ds_bpermute_b32 v33, v6, v32
	s_waitcnt lgkmcnt(0)
	v_add_f32_e32 v32, v32, v33
	ds_bpermute_b32 v33, v7, v32
	s_waitcnt lgkmcnt(0)
	v_add_f32_e32 v32, v32, v33
	ds_bpermute_b32 v33, v8, v32
	s_waitcnt lgkmcnt(0)
	v_add_f32_e32 v32, v32, v33
	ds_bpermute_b32 v33, v9, v32
	s_waitcnt lgkmcnt(0)
	v_add_f32_e32 v32, v32, v33
	ds_bpermute_b32 v33, v10, v32
	s_waitcnt lgkmcnt(0)
	v_add_f32_e32 v32, v32, v33
	v_fmamk_f32 v32, v32, 0x3a800000, v11
	v_mul_f32_e32 v33, 0x4b800000, v32
	v_cmp_gt_f32_e32 vcc, s1, v32
	s_nop 1
	v_cndmask_b32_e32 v32, v32, v33, vcc
	v_rsq_f32_e32 v32, v32
	s_nop 0
	v_mul_f32_e32 v33, 0x45800000, v32
	v_cndmask_b32_e32 v32, v32, v33, vcc
	s_nop 0
	v_pk_mul_f32 v[68:69], v[68:69], v[32:33] op_sel_hi:[1,0]
	v_pk_mul_f32 v[70:71], v[70:71], v[32:33] op_sel_hi:[1,0]
	v_pk_mul_f32 v[68:69], v[48:49], v[68:69]
	v_pk_mul_f32 v[70:71], v[50:51], v[70:71]
	global_store_dwordx4 v[64:65], v[68:71], off offset:-2048
	v_pk_mul_f32 v[72:73], v[72:73], v[32:33] op_sel_hi:[1,0]
	v_pk_mul_f32 v[74:75], v[74:75], v[32:33] op_sel_hi:[1,0]
	v_pk_mul_f32 v[72:73], v[52:53], v[72:73]
	v_pk_mul_f32 v[74:75], v[54:55], v[74:75]
	global_store_dwordx4 v[64:65], v[72:75], off offset:-1024
	v_pk_mul_f32 v[76:77], v[76:77], v[32:33] op_sel_hi:[1,0]
	v_pk_mul_f32 v[78:79], v[78:79], v[32:33] op_sel_hi:[1,0]
	v_pk_mul_f32 v[76:77], v[56:57], v[76:77]
	v_pk_mul_f32 v[78:79], v[58:59], v[78:79]
	global_store_dwordx4 v[64:65], v[76:79], off
	v_pk_mul_f32 v[80:81], v[80:81], v[32:33] op_sel_hi:[1,0]
	v_pk_mul_f32 v[82:83], v[82:83], v[32:33] op_sel_hi:[1,0]
	v_pk_mul_f32 v[80:81], v[60:61], v[80:81]
	v_pk_mul_f32 v[82:83], v[62:63], v[82:83]
	global_store_dwordx4 v[64:65], v[80:83], off offset:1024
	s_branch .Lfin_A
; DI float shx(float v, int lane, int m) { return __int_as_float(__builtin_amdgcn_ds_bpermute((lane ^ m) << 2, __float_as_int(v))); }
; DI void phase_final(const int wv_, const Params& p) {
;     ...
;   for (int R = bid_ * 8 + wave; R < NB * SEQ; R += nblk_ * 8) {
;     float4* row = (float4*)(p.out + (size_t)R * 1024);
;     float4 v[4]; float ss = 0.f;
; #pragma unroll
;     for (int i = 0; i < 4; ++i) { v[i] = row[lane + i * 64]; ss += v[i].x * v[i].x + v[i].y * v[i].y + v[i].z * v[i].z + v[i].w * v[i].w; }
; #pragma unroll
;     for (int o = 32; o >= 1; o >>= 1) ss += shx(ss, lane, o);
;     float sc = rsqrtf(ss * (1.f / 1024.f) + 1e-6f);
; #pragma unroll
;     for (int i = 0; i < 4; ++i) {
;       float4 gg = ((const float4*)p.final_g)[lane + i * 64];
;       row[lane + i * 64] = make_float4(v[i].x * sc * gg.x, v[i].y * sc * gg.y, v[i].z * sc * gg.z, v[i].w * sc * gg.w);
;     }
.Lfin_A_last:
	s_waitcnt vmcnt(0)
	v_mul_f32_e32 v34, v12, v12
	v_fmac_f32_e32 v34, v13, v13
	v_fmac_f32_e32 v34, v14, v14
	v_fmac_f32_e32 v34, v15, v15
	v_fmac_f32_e32 v34, v16, v16
	v_fmac_f32_e32 v34, v17, v17
	v_fmac_f32_e32 v34, v18, v18
	v_fmac_f32_e32 v34, v19, v19
	v_fmac_f32_e32 v34, v20, v20
	v_fmac_f32_e32 v34, v21, v21
	v_fmac_f32_e32 v34, v22, v22
	v_fmac_f32_e32 v34, v23, v23
	v_fmac_f32_e32 v34, v24, v24
	v_fmac_f32_e32 v34, v25, v25
	v_fmac_f32_e32 v34, v26, v26
	v_fmac_f32_e32 v34, v27, v27
	v_mov_b32_e32 v32, v34
	ds_bpermute_b32 v33, v5, v32
	s_waitcnt lgkmcnt(0)
	v_add_f32_e32 v32, v32, v33
	ds_bpermute_b32 v33, v6, v32
	s_waitcnt lgkmcnt(0)
	v_add_f32_e32 v32, v32, v33
	ds_bpermute_b32 v33, v7, v32
	s_waitcnt lgkmcnt(0)
	v_add_f32_e32 v32, v32, v33
	ds_bpermute_b32 v33, v8, v32
	s_waitcnt lgkmcnt(0)
	v_add_f32_e32 v32, v32, v33
	ds_bpermute_b32 v33, v9, v32
	s_waitcnt lgkmcnt(0)
	v_add_f32_e32 v32, v32, v33
	ds_bpermute_b32 v33, v10, v32
	s_waitcnt lgkmcnt(0)
	v_add_f32_e32 v32, v32, v33
	v_fmamk_f32 v32, v32, 0x3a800000, v11
	v_mul_f32_e32 v33, 0x4b800000, v32
	v_cmp_gt_f32_e32 vcc, s1, v32
	s_nop 1
	v_cndmask_b32_e32 v32, v32, v33, vcc
	v_rsq_f32_e32 v32, v32
	s_nop 0
	v_mul_f32_e32 v33, 0x45800000, v32
	v_cndmask_b32_e32 v32, v32, v33, vcc
	s_nop 0
	v_pk_mul_f32 v[12:13], v[12:13], v[32:33] op_sel_hi:[1,0]
	v_pk_mul_f32 v[14:15], v[14:15], v[32:33] op_sel_hi:[1,0]
	v_pk_mul_f32 v[12:13], v[48:49], v[12:13]
	v_pk_mul_f32 v[14:15], v[50:51], v[14:15]
	global_store_dwordx4 v[2:3], v[12:15], off offset:-2048
	v_pk_mul_f32 v[16:17], v[16:17], v[32:33] op_sel_hi:[1,0]
	v_pk_mul_f32 v[18:19], v[18:19], v[32:33] op_sel_hi:[1,0]
	v_pk_mul_f32 v[16:17], v[52:53], v[16:17]
	v_pk_mul_f32 v[18:19], v[54:55], v[18:19]
	global_store_dwordx4 v[2:3], v[16:19], off offset:-1024
	v_pk_mul_f32 v[20:21], v[20:21], v[32:33] op_sel_hi:[1,0]
	v_pk_mul_f32 v[22:23], v[22:23], v[32:33] op_sel_hi:[1,0]
	v_pk_mul_f32 v[20:21], v[56:57], v[20:21]
	v_pk_mul_f32 v[22:23], v[58:59], v[22:23]
	global_store_dwordx4 v[2:3], v[20:23], off
	v_pk_mul_f32 v[24:25], v[24:25], v[32:33] op_sel_hi:[1,0]
	v_pk_mul_f32 v[26:27], v[26:27], v[32:33] op_sel_hi:[1,0]
	v_pk_mul_f32 v[24:25], v[60:61], v[24:25]
	v_pk_mul_f32 v[26:27], v[62:63], v[26:27]
	global_store_dwordx4 v[2:3], v[24:27], off offset:1024
	s_branch .LBB0_1064
.Lfin_B_last:
	s_waitcnt vmcnt(0)
	v_mul_f32_e32 v34, v68, v68
	v_fmac_f32_e32 v34, v69, v69
	v_fmac_f32_e32 v34, v70, v70
	v_fmac_f32_e32 v34, v71, v71
	v_fmac_f32_e32 v34, v72, v72
	v_fmac_f32_e32 v34, v73, v73
	v_fmac_f32_e32 v34, v74, v74
	v_fmac_f32_e32 v34, v75, v75
	v_fmac_f32_e32 v34, v76, v76
	v_fmac_f32_e32 v34, v77, v77
	v_fmac_f32_e32 v34, v78, v78
	v_fmac_f32_e32 v34, v79, v79
	v_fmac_f32_e32 v34, v80, v80
	v_fmac_f32_e32 v34, v81, v81
	v_fmac_f32_e32 v34, v82, v82
	v_fmac_f32_e32 v34, v83, v83
	v_mov_b32_e32 v32, v34
	ds_bpermute_b32 v33, v5, v32
	s_waitcnt lgkmcnt(0)
	v_add_f32_e32 v32, v32, v33
	ds_bpermute_b32 v33, v6, v32
	s_waitcnt lgkmcnt(0)
	v_add_f32_e32 v32, v32, v33
	ds_bpermute_b32 v33, v7, v32
	s_waitcnt lgkmcnt(0)
	v_add_f32_e32 v32, v32, v33
	ds_bpermute_b32 v33, v8, v32
	s_waitcnt lgkmcnt(0)
	v_add_f32_e32 v32, v32, v33
	ds_bpermute_b32 v33, v9, v32
	s_waitcnt lgkmcnt(0)
	v_add_f32_e32 v32, v32, v33
	ds_bpermute_b32 v33, v10, v32
	s_waitcnt lgkmcnt(0)
	v_add_f32_e32 v32, v32, v33
	v_fmamk_f32 v32, v32, 0x3a800000, v11
	v_mul_f32_e32 v33, 0x4b800000, v32
	v_cmp_gt_f32_e32 vcc, s1, v32
	s_nop 1
	v_cndmask_b32_e32 v32, v32, v33, vcc
	v_rsq_f32_e32 v32, v32
	s_nop 0
	v_mul_f32_e32 v33, 0x45800000, v32
	v_cndmask_b32_e32 v32, v32, v33, vcc
	s_nop 0
	v_pk_mul_f32 v[68:69], v[68:69], v[32:33] op_sel_hi:[1,0]
	v_pk_mul_f32 v[70:71], v[70:71], v[32:33] op_sel_hi:[1,0]
	v_pk_mul_f32 v[68:69], v[48:49], v[68:69]
	v_pk_mul_f32 v[70:71], v[50:51], v[70:71]
	global_store_dwordx4 v[64:65], v[68:71], off offset:-2048
	v_pk_mul_f32 v[72:73], v[72:73], v[32:33] op_sel_hi:[1,0]
	v_pk_mul_f32 v[74:75], v[74:75], v[32:33] op_sel_hi:[1,0]
	v_pk_mul_f32 v[72:73], v[52:53], v[72:73]
	v_pk_mul_f32 v[74:75], v[54:55], v[74:75]
	global_store_dwordx4 v[64:65], v[72:75], off offset:-1024
	v_pk_mul_f32 v[76:77], v[76:77], v[32:33] op_sel_hi:[1,0]
	v_pk_mul_f32 v[78:79], v[78:79], v[32:33] op_sel_hi:[1,0]
	v_pk_mul_f32 v[76:77], v[56:57], v[76:77]
	v_pk_mul_f32 v[78:79], v[58:59], v[78:79]
	global_store_dwordx4 v[64:65], v[76:79], off
	v_pk_mul_f32 v[80:81], v[80:81], v[32:33] op_sel_hi:[1,0]
	v_pk_mul_f32 v[82:83], v[82:83], v[32:33] op_sel_hi:[1,0]
	v_pk_mul_f32 v[80:81], v[60:61], v[80:81]
	v_pk_mul_f32 v[82:83], v[62:63], v[82:83]
	global_store_dwordx4 v[64:65], v[80:83], off offset:1024
